# phase 1: nt (non-temporal) loads for the read-once x / ctx row streams of the norm loops; plus context norm 4-way split
# speedup vs baseline: 1.0113x; 1.0067x over previous
.LBB0_227:
	s_add_u32 s2, s22, 0x30bc000
	s_addc_u32 s3, s23, 0
	s_lshl_b32 s29, s25, 3
	s_abs_i32 s28, s29
	v_cvt_f32_u32_e32 v0, s28
	s_add_i32 s0, s29, 0x7fff
	s_sub_i32 s10, 0xffff8001, s29
	s_ashr_i32 s1, s0, 31
	v_rcp_iflag_f32_e32 v0, v0
	s_max_i32 s0, s0, s10
	s_sub_i32 s10, 0, s28
	s_ashr_i32 s30, s29, 31
	v_mul_f32_e32 v0, 0x4f7ffffe, v0
	v_cvt_u32_f32_e32 v0, v0
	s_xor_b32 s1, s1, s30
	v_lshrrev_b32_e32 v1, 6, v160
	v_lshl_add_u32 v99, s24, 3, v1
	v_readfirstlane_b32 s31, v0
	s_mul_i32 s10, s10, s31
	s_mul_hi_u32 s10, s31, s10
	s_add_i32 s31, s31, s10
	s_mul_hi_u32 s10, s0, s31
	s_mul_i32 s11, s10, s28
	s_sub_i32 s0, s0, s11
	s_add_i32 s11, s10, 1
	s_sub_i32 s12, s0, s28
	s_cmp_ge_u32 s0, s28
	s_cselect_b32 s10, s11, s10
	s_cselect_b32 s0, s12, s0
	s_add_i32 s11, s10, 1
	s_cmp_ge_u32 s0, s28
	s_cselect_b32 s0, s11, s10
	s_xor_b32 s0, s0, s1
	s_sub_i32 s0, s0, s1
	v_mul_lo_u32 v48, s0, v99
	v_add_u32_e32 v0, s0, v48
	v_min_i32_e32 v103, 0x8000, v0
	v_cmp_lt_i32_e32 vcc, v48, v103
	s_and_saveexec_b64 s[10:11], vcc
	s_cbranch_execz .LBB0_256
	v_ashrrev_i32_e32 v49, 31, v48
	v_readlane_b32 s36, v240, 8
	v_lshlrev_b32_e32 v2, 2, v160
	v_lshlrev_b64 v[0:1], 12, v[48:49]
	v_readlane_b32 s37, v240, 9
	v_and_b32_e32 v52, 0xfc, v2
	v_mov_b32_e32 v97, 0
	v_lshl_add_u64 v[0:1], s[36:37], 0, v[0:1]
	v_lshlrev_b32_e32 v96, 2, v52
	v_lshl_add_u64 v[12:13], v[0:1], 0, v[96:97]
	global_load_dwordx4 v[0:3], v[12:13], off nt
	global_load_dwordx4 v[4:7], v[12:13], off offset:1024 nt
	global_load_dwordx4 v[8:11], v[12:13], off offset:2048 nt
	s_nop 0
	global_load_dwordx4 v[12:15], v[12:13], off offset:3072 nt
	v_add_u32_e32 v32, 1, v48
	v_cmp_lt_i32_e32 vcc, v32, v103
	v_readlane_b32 s38, v240, 10
	v_readlane_b32 s39, v240, 11
	v_readlane_b32 s40, v240, 12
	v_readlane_b32 s41, v240, 13
	v_readlane_b32 s42, v240, 14
	v_readlane_b32 s43, v240, 15
	v_readlane_b32 s44, v240, 16
	v_readlane_b32 s45, v240, 17
	v_readlane_b32 s46, v240, 18
	v_readlane_b32 s47, v240, 19
	v_readlane_b32 s48, v240, 20
	v_readlane_b32 s49, v240, 21
	v_readlane_b32 s50, v240, 22
	v_readlane_b32 s51, v240, 23
	s_and_saveexec_b64 s[0:1], vcc
	s_cbranch_execz .LBB0_230
	v_ashrrev_i32_e32 v33, 31, v32
	v_readlane_b32 s36, v240, 8
	s_waitcnt vmcnt(12)
	v_lshlrev_b64 v[16:17], 12, v[32:33]
	v_readlane_b32 s37, v240, 9
	v_readlane_b32 s38, v240, 10
	v_readlane_b32 s39, v240, 11
	v_lshl_add_u64 v[16:17], s[36:37], 0, v[16:17]
	v_lshl_add_u64 v[28:29], v[16:17], 0, v[96:97]
	global_load_dwordx4 v[16:19], v[28:29], off nt
	global_load_dwordx4 v[20:23], v[28:29], off offset:1024 nt
	global_load_dwordx4 v[24:27], v[28:29], off offset:2048 nt
	s_nop 0
	global_load_dwordx4 v[28:31], v[28:29], off offset:3072 nt
	v_readlane_b32 s40, v240, 12
	v_readlane_b32 s41, v240, 13
	v_readlane_b32 s42, v240, 14
	v_readlane_b32 s43, v240, 15
	v_readlane_b32 s44, v240, 16
	v_readlane_b32 s45, v240, 17
	v_readlane_b32 s46, v240, 18
	v_readlane_b32 s47, v240, 19
	v_readlane_b32 s48, v240, 20
	v_readlane_b32 s49, v240, 21
	v_readlane_b32 s50, v240, 22
	v_readlane_b32 s51, v240, 23
.LBB0_230:
	s_or_b64 exec, exec, s[0:1]
	v_add_u32_e32 v50, 2, v48
	v_cmp_lt_i32_e32 vcc, v50, v103
	s_and_saveexec_b64 s[0:1], vcc
	s_cbranch_execz .LBB0_232
	v_ashrrev_i32_e32 v51, 31, v50
	v_readlane_b32 s36, v240, 8
	v_lshlrev_b64 v[32:33], 12, v[50:51]
	v_readlane_b32 s37, v240, 9
	v_mov_b32_e32 v97, 0
	v_readlane_b32 s38, v240, 10
	v_lshl_add_u64 v[32:33], s[36:37], 0, v[32:33]
	v_lshl_add_u64 v[44:45], v[32:33], 0, v[96:97]
	global_load_dwordx4 v[32:35], v[44:45], off nt
	global_load_dwordx4 v[36:39], v[44:45], off offset:1024 nt
	global_load_dwordx4 v[40:43], v[44:45], off offset:2048 nt
	s_nop 0
	global_load_dwordx4 v[44:47], v[44:45], off offset:3072 nt
	v_readlane_b32 s39, v240, 11
	v_readlane_b32 s40, v240, 12
	v_readlane_b32 s41, v240, 13
	v_readlane_b32 s42, v240, 14
	v_readlane_b32 s43, v240, 15
	v_readlane_b32 s44, v240, 16
	v_readlane_b32 s45, v240, 17
	v_readlane_b32 s46, v240, 18
	v_readlane_b32 s47, v240, 19
	v_readlane_b32 s48, v240, 20
	v_readlane_b32 s49, v240, 21
	v_readlane_b32 s50, v240, 22
	v_readlane_b32 s51, v240, 23

.LBB0_235:
	v_add_u32_e32 v134, -3, v118
	v_cmp_lt_i32_e32 vcc, v134, v103
	s_and_saveexec_b64 s[0:1], vcc
	s_cbranch_execz .LBB0_237
	global_load_dwordx4 v[60:63], v[110:111], off offset:-3072 nt
	global_load_dwordx4 v[56:59], v[110:111], off offset:-2048 nt
	global_load_dwordx4 v[52:55], v[110:111], off offset:-1024 nt
	global_load_dwordx4 v[48:51], v[110:111], off nt
.LBB0_237:
	s_or_b64 exec, exec, s[0:1]
	v_add_u32_e32 v119, -6, v118
	v_ashrrev_i32_e32 v119, 12, v119
	v_cmp_ne_u32_e64 s[0:1], v119, v132
	s_and_saveexec_b64 s[24:25], s[0:1]
	s_cbranch_execz .LBB0_239
	v_mul_hi_i32_i24_e32 v65, 0x6000, v119
	v_mul_i32_i24_e32 v64, 0x6000, v119
	v_lshl_add_u64 v[64:65], s[88:89], 0, v[64:65]
	v_lshl_add_u64 v[66:67], v[64:65], 0, s[14:15]
	v_lshl_add_u64 v[68:69], v[66:67], 0, v[96:97]
	global_load_dwordx4 v[80:83], v[68:69], off nt
	v_lshlrev_b32_e32 v68, 2, v102
	v_mov_b32_e32 v69, v97
	v_lshl_add_u64 v[68:69], v[66:67], 0, v[68:69]
	global_load_dwordx4 v[84:87], v[68:69], off nt
	v_lshlrev_b32_e32 v68, 2, v98
	v_mov_b32_e32 v69, v97
	v_lshl_add_u64 v[68:69], v[66:67], 0, v[68:69]
	global_load_dwordx4 v[88:91], v[68:69], off nt
	v_lshlrev_b32_e32 v68, 2, v104
	v_mov_b32_e32 v69, v97
	v_lshl_add_u64 v[66:67], v[66:67], 0, v[68:69]
	global_load_dwordx4 v[92:95], v[66:67], off nt
	global_load_dwordx4 v[122:125], v[106:107], off nt
	global_load_dwordx4 v[136:139], v[106:107], off offset:1024 nt
	v_lshl_add_u64 v[76:77], v[64:65], 0, v[96:97]
	global_load_dwordx4 v[140:143], v[106:107], off offset:2048 nt
	global_load_dwordx4 v[64:67], v[76:77], off nt
	global_load_dwordx4 v[144:147], v[106:107], off offset:3072 nt
	global_load_dwordx4 v[68:71], v[76:77], off offset:1024 nt
	global_load_dwordx4 v[72:75], v[76:77], off offset:2048 nt
	s_nop 0
	global_load_dwordx4 v[76:79], v[76:77], off offset:3072 nt
	v_mov_b32_e32 v132, v119
	s_waitcnt vmcnt(11)
	v_pk_add_f32 v[82:83], v[82:83], 1.0 op_sel_hi:[1,0]
	v_pk_add_f32 v[80:81], v[80:81], 1.0 op_sel_hi:[1,0]
	s_waitcnt vmcnt(10)
	v_pk_add_f32 v[86:87], v[86:87], 1.0 op_sel_hi:[1,0]
	v_pk_add_f32 v[84:85], v[84:85], 1.0 op_sel_hi:[1,0]
	s_waitcnt vmcnt(9)
	v_pk_add_f32 v[90:91], v[90:91], 1.0 op_sel_hi:[1,0]
	v_pk_add_f32 v[88:89], v[88:89], 1.0 op_sel_hi:[1,0]
	s_waitcnt vmcnt(8)
	v_pk_add_f32 v[94:95], v[94:95], 1.0 op_sel_hi:[1,0]
	v_pk_add_f32 v[92:93], v[92:93], 1.0 op_sel_hi:[1,0]
	s_waitcnt vmcnt(7)
	v_pk_mul_f32 v[82:83], v[124:125], v[82:83]
	v_pk_mul_f32 v[80:81], v[122:123], v[80:81]
	s_waitcnt vmcnt(6)
	v_pk_mul_f32 v[86:87], v[138:139], v[86:87]
	v_pk_mul_f32 v[84:85], v[136:137], v[84:85]
	s_waitcnt vmcnt(5)
	v_pk_mul_f32 v[90:91], v[142:143], v[90:91]
	v_pk_mul_f32 v[88:89], v[140:141], v[88:89]
	s_waitcnt vmcnt(3)
	v_pk_mul_f32 v[94:95], v[146:147], v[94:95]
	v_pk_mul_f32 v[92:93], v[144:145], v[92:93]
.LBB0_239:
	s_or_b64 exec, exec, s[24:25]
	s_waitcnt vmcnt(2)
	v_mov_b32_e32 v124, v5
	v_mov_b32_e32 v125, v1
	v_mov_b32_e32 v122, v4
	v_mov_b32_e32 v123, v0
	v_pk_mul_f32 v[124:125], v[124:125], v[124:125]
	s_waitcnt vmcnt(0)
	v_mov_b32_e32 v136, v13
	v_pk_fma_f32 v[122:123], v[122:123], v[122:123], v[124:125]
	v_mov_b32_e32 v124, v6
	v_mov_b32_e32 v125, v2
	v_pk_fma_f32 v[122:123], v[124:125], v[124:125], v[122:123]
	v_mov_b32_e32 v124, v7
	v_mov_b32_e32 v125, v3
	v_mov_b32_e32 v137, v9
	v_pk_fma_f32 v[122:123], v[124:125], v[124:125], v[122:123]
	v_mov_b32_e32 v124, v12
	v_mov_b32_e32 v125, v8
	v_pk_mul_f32 v[136:137], v[136:137], v[136:137]
	v_add_f32_e32 v119, v122, v123
	v_pk_fma_f32 v[124:125], v[124:125], v[124:125], v[136:137]
	v_mov_b32_e32 v136, v14
	v_mov_b32_e32 v137, v10
	v_pk_fma_f32 v[124:125], v[136:137], v[136:137], v[124:125]
	v_mov_b32_e32 v136, v15
	v_mov_b32_e32 v137, v11
	v_pk_fma_f32 v[124:125], v[136:137], v[136:137], v[124:125]
	v_add_u32_e32 v133, -2, v118
	v_add_f32_e32 v119, v125, v119
	v_add_f32_e32 v119, v124, v119
	ds_bpermute_b32 v122, v105, v119
	s_waitcnt lgkmcnt(0)
	v_add_f32_e32 v119, v119, v122
	ds_bpermute_b32 v122, v126, v119
	s_waitcnt lgkmcnt(0)
	v_add_f32_e32 v119, v119, v122
	ds_bpermute_b32 v122, v127, v119
	s_waitcnt lgkmcnt(0)
	v_add_f32_e32 v119, v119, v122
	ds_bpermute_b32 v122, v128, v119
	s_waitcnt lgkmcnt(0)
	v_add_f32_e32 v119, v119, v122
	ds_bpermute_b32 v122, v129, v119
	s_waitcnt lgkmcnt(0)
	v_add_f32_e32 v119, v119, v122
	ds_bpermute_b32 v122, v130, v119
	s_waitcnt lgkmcnt(0)
	v_add_f32_e32 v119, v119, v122
	v_fmamk_f32 v119, v119, 0x3a800000, v131
	v_mul_f32_e32 v122, 0x4b800000, v119
	v_cmp_gt_f32_e64 s[0:1], s42, v119
	s_nop 1
	v_cndmask_b32_e64 v119, v119, v122, s[0:1]
	v_rsq_f32_e32 v119, v119
	v_lshl_add_u64 v[122:123], v[120:121], 0, v[112:113]
	v_mul_f32_e32 v124, 0x45800000, v119
	v_cndmask_b32_e64 v124, v119, v124, s[0:1]
	v_pk_mul_f32 v[136:137], v[0:1], v[124:125] op_sel_hi:[1,0]
	v_pk_mul_f32 v[138:139], v[2:3], v[124:125] op_sel_hi:[1,0]
	v_pk_fma_f32 v[136:137], v[80:81], v[136:137], v[64:65]
	v_pk_fma_f32 v[138:139], v[82:83], v[138:139], v[66:67]
	v_add_co_u32_e64 v122, s[0:1], s43, v122
	v_cvt_pk_bf16_f32 v136, v136, v137
	v_cvt_pk_bf16_f32 v137, v138, v139
	v_addc_co_u32_e64 v123, s[0:1], 0, v123, s[0:1]
	global_store_dwordx2 v[122:123], v[136:137], off
	v_pk_mul_f32 v[136:137], v[4:5], v[124:125] op_sel_hi:[1,0]
	v_pk_mul_f32 v[138:139], v[6:7], v[124:125] op_sel_hi:[1,0]
	v_pk_fma_f32 v[136:137], v[84:85], v[136:137], v[68:69]
	v_pk_fma_f32 v[138:139], v[86:87], v[138:139], v[70:71]
	v_cvt_pk_bf16_f32 v136, v136, v137
	v_cvt_pk_bf16_f32 v137, v138, v139
	global_store_dwordx2 v[122:123], v[136:137], off offset:512
	v_pk_mul_f32 v[136:137], v[8:9], v[124:125] op_sel_hi:[1,0]
	v_pk_mul_f32 v[138:139], v[10:11], v[124:125] op_sel_hi:[1,0]
	v_pk_fma_f32 v[136:137], v[88:89], v[136:137], v[72:73]
	v_pk_fma_f32 v[138:139], v[90:91], v[138:139], v[74:75]
	v_cvt_pk_bf16_f32 v136, v136, v137
	v_cvt_pk_bf16_f32 v137, v138, v139
	global_store_dwordx2 v[122:123], v[136:137], off offset:1024
	v_pk_mul_f32 v[136:137], v[12:13], v[124:125] op_sel_hi:[1,0]
	v_pk_mul_f32 v[124:125], v[14:15], v[124:125] op_sel_hi:[1,0]
	v_pk_fma_f32 v[136:137], v[92:93], v[136:137], v[76:77]
	v_pk_fma_f32 v[124:125], v[94:95], v[124:125], v[78:79]
	v_cvt_pk_bf16_f32 v136, v136, v137
	v_cvt_pk_bf16_f32 v137, v124, v125
	global_store_dwordx2 v[122:123], v[136:137], off offset:1536
	v_add_u32_e32 v122, -5, v118
	v_cmp_lt_i32_e64 s[0:1], v122, v103
	s_and_saveexec_b64 s[24:25], s[0:1]
	s_cbranch_execz .LBB0_245
	v_cmp_lt_i32_e64 s[0:1], v133, v103
	s_and_saveexec_b64 s[26:27], s[0:1]
	s_cbranch_execz .LBB0_242
	global_load_dwordx4 v[0:3], v[116:117], off offset:-2048 nt
	global_load_dwordx4 v[4:7], v[116:117], off offset:-1024 nt
	global_load_dwordx4 v[8:11], v[116:117], off nt
	global_load_dwordx4 v[12:15], v[116:117], off offset:1024 nt
.LBB0_242:
	s_or_b64 exec, exec, s[26:27]
	v_ashrrev_i32_e32 v119, 12, v122
	v_cmp_ne_u32_e64 s[0:1], v119, v132
	s_and_saveexec_b64 s[26:27], s[0:1]
	s_cbranch_execz .LBB0_244
	v_mul_hi_i32_i24_e32 v65, 0x6000, v119
	v_mul_i32_i24_e32 v64, 0x6000, v119
	v_lshl_add_u64 v[64:65], s[88:89], 0, v[64:65]
	v_lshl_add_u64 v[66:67], v[64:65], 0, s[14:15]
	v_lshl_add_u64 v[68:69], v[66:67], 0, v[96:97]
	global_load_dwordx4 v[80:83], v[68:69], off nt
	v_lshlrev_b32_e32 v68, 2, v102
	v_mov_b32_e32 v69, v97
	v_lshl_add_u64 v[68:69], v[66:67], 0, v[68:69]
	global_load_dwordx4 v[84:87], v[68:69], off nt
	v_lshlrev_b32_e32 v68, 2, v98
	v_mov_b32_e32 v69, v97
	v_lshl_add_u64 v[68:69], v[66:67], 0, v[68:69]
	global_load_dwordx4 v[88:91], v[68:69], off nt
	v_lshlrev_b32_e32 v68, 2, v104
	v_mov_b32_e32 v69, v97
	v_lshl_add_u64 v[66:67], v[66:67], 0, v[68:69]
	global_load_dwordx4 v[92:95], v[66:67], off nt
	global_load_dwordx4 v[136:139], v[106:107], off nt
	global_load_dwordx4 v[140:143], v[106:107], off offset:1024 nt
	v_lshl_add_u64 v[76:77], v[64:65], 0, v[96:97]
	global_load_dwordx4 v[144:147], v[106:107], off offset:2048 nt
	global_load_dwordx4 v[64:67], v[76:77], off nt
	global_load_dwordx4 v[148:151], v[106:107], off offset:3072 nt
	global_load_dwordx4 v[68:71], v[76:77], off offset:1024 nt
	global_load_dwordx4 v[72:75], v[76:77], off offset:2048 nt
	s_nop 0
	global_load_dwordx4 v[76:79], v[76:77], off offset:3072 nt
	v_mov_b32_e32 v132, v119
	s_waitcnt vmcnt(11)
	v_pk_add_f32 v[82:83], v[82:83], 1.0 op_sel_hi:[1,0]
	v_pk_add_f32 v[80:81], v[80:81], 1.0 op_sel_hi:[1,0]
	s_waitcnt vmcnt(10)
	v_pk_add_f32 v[86:87], v[86:87], 1.0 op_sel_hi:[1,0]
	v_pk_add_f32 v[84:85], v[84:85], 1.0 op_sel_hi:[1,0]
	s_waitcnt vmcnt(9)
	v_pk_add_f32 v[90:91], v[90:91], 1.0 op_sel_hi:[1,0]
	v_pk_add_f32 v[88:89], v[88:89], 1.0 op_sel_hi:[1,0]
	s_waitcnt vmcnt(8)
	v_pk_add_f32 v[94:95], v[94:95], 1.0 op_sel_hi:[1,0]
	v_pk_add_f32 v[92:93], v[92:93], 1.0 op_sel_hi:[1,0]
	s_waitcnt vmcnt(7)
	v_pk_mul_f32 v[82:83], v[138:139], v[82:83]
	v_pk_mul_f32 v[80:81], v[136:137], v[80:81]
	s_waitcnt vmcnt(6)
	v_pk_mul_f32 v[86:87], v[142:143], v[86:87]
	v_pk_mul_f32 v[84:85], v[140:141], v[84:85]
	s_waitcnt vmcnt(5)
	v_pk_mul_f32 v[90:91], v[146:147], v[90:91]
	v_pk_mul_f32 v[88:89], v[144:145], v[88:89]
	s_waitcnt vmcnt(3)
	v_pk_mul_f32 v[94:95], v[150:151], v[94:95]
	v_pk_mul_f32 v[92:93], v[148:149], v[92:93]

.LBB0_245:
	s_or_b64 exec, exec, s[24:25]
	v_add_u32_e32 v122, -4, v118
	v_cmp_lt_i32_e64 s[0:1], v122, v103
	s_and_saveexec_b64 s[24:25], s[0:1]
	s_cbranch_execz .LBB0_251
	v_add_u32_e32 v124, -1, v118
	v_cmp_lt_i32_e64 s[0:1], v124, v103
	s_and_saveexec_b64 s[26:27], s[0:1]
	s_cbranch_execz .LBB0_248
	v_ashrrev_i32_e32 v125, 31, v124
	v_lshlrev_b64 v[16:17], 12, v[124:125]
	v_lshl_add_u64 v[28:29], v[108:109], 0, v[16:17]
	global_load_dwordx4 v[16:19], v[28:29], off nt
	global_load_dwordx4 v[20:23], v[28:29], off offset:1024 nt
	global_load_dwordx4 v[24:27], v[28:29], off offset:2048 nt
	s_nop 0
	global_load_dwordx4 v[28:31], v[28:29], off offset:3072 nt

.LBB0_251:
	s_or_b64 exec, exec, s[24:25]
	s_and_saveexec_b64 s[0:1], vcc
	s_cbranch_execz .LBB0_234
	v_cmp_lt_i32_e32 vcc, v118, v103
	s_and_saveexec_b64 s[24:25], vcc
	s_cbranch_execz .LBB0_254
	v_ashrrev_i32_e32 v119, 31, v118
	v_lshlrev_b64 v[32:33], 12, v[118:119]
	v_lshl_add_u64 v[44:45], v[108:109], 0, v[32:33]
	global_load_dwordx4 v[32:35], v[44:45], off nt
	global_load_dwordx4 v[36:39], v[44:45], off offset:1024 nt
	global_load_dwordx4 v[40:43], v[44:45], off offset:2048 nt
	s_nop 0
	global_load_dwordx4 v[44:47], v[44:45], off offset:3072 nt
.LBB0_254:
	s_or_b64 exec, exec, s[24:25]
	v_ashrrev_i32_e32 v119, 12, v134
	v_cmp_ne_u32_e32 vcc, v119, v132
	s_and_saveexec_b64 s[24:25], vcc
	s_cbranch_execz .LBB0_233
	v_mul_hi_i32_i24_e32 v65, 0x6000, v119
	v_mul_i32_i24_e32 v64, 0x6000, v119
	v_lshl_add_u64 v[64:65], s[88:89], 0, v[64:65]
	v_lshl_add_u64 v[66:67], v[64:65], 0, s[14:15]
	v_lshl_add_u64 v[68:69], v[66:67], 0, v[96:97]
	global_load_dwordx4 v[80:83], v[68:69], off nt
	v_lshlrev_b32_e32 v68, 2, v102
	v_mov_b32_e32 v69, v97
	v_lshl_add_u64 v[68:69], v[66:67], 0, v[68:69]
	global_load_dwordx4 v[84:87], v[68:69], off nt
	v_lshlrev_b32_e32 v68, 2, v98
	v_mov_b32_e32 v69, v97
	v_lshl_add_u64 v[68:69], v[66:67], 0, v[68:69]
	global_load_dwordx4 v[88:91], v[68:69], off nt
	v_lshlrev_b32_e32 v68, 2, v104
	v_mov_b32_e32 v69, v97
	v_lshl_add_u64 v[66:67], v[66:67], 0, v[68:69]
	global_load_dwordx4 v[92:95], v[66:67], off nt
	global_load_dwordx4 v[122:125], v[106:107], off nt
	global_load_dwordx4 v[134:137], v[106:107], off offset:1024 nt
	v_lshl_add_u64 v[76:77], v[64:65], 0, v[96:97]
	global_load_dwordx4 v[138:141], v[106:107], off offset:2048 nt
	global_load_dwordx4 v[64:67], v[76:77], off nt
	global_load_dwordx4 v[142:145], v[106:107], off offset:3072 nt
	global_load_dwordx4 v[68:71], v[76:77], off offset:1024 nt
	global_load_dwordx4 v[72:75], v[76:77], off offset:2048 nt
	s_nop 0
	global_load_dwordx4 v[76:79], v[76:77], off offset:3072 nt
	v_mov_b32_e32 v132, v119
	s_waitcnt vmcnt(11)
	v_pk_add_f32 v[82:83], v[82:83], 1.0 op_sel_hi:[1,0]
	v_pk_add_f32 v[80:81], v[80:81], 1.0 op_sel_hi:[1,0]
	s_waitcnt vmcnt(10)
	v_pk_add_f32 v[86:87], v[86:87], 1.0 op_sel_hi:[1,0]
	v_pk_add_f32 v[84:85], v[84:85], 1.0 op_sel_hi:[1,0]
	s_waitcnt vmcnt(9)
	v_pk_add_f32 v[90:91], v[90:91], 1.0 op_sel_hi:[1,0]
	v_pk_add_f32 v[88:89], v[88:89], 1.0 op_sel_hi:[1,0]
	s_waitcnt vmcnt(8)
	v_pk_add_f32 v[94:95], v[94:95], 1.0 op_sel_hi:[1,0]
	v_pk_add_f32 v[92:93], v[92:93], 1.0 op_sel_hi:[1,0]
	s_waitcnt vmcnt(7)
	v_pk_mul_f32 v[82:83], v[124:125], v[82:83]
	v_pk_mul_f32 v[80:81], v[122:123], v[80:81]
	s_waitcnt vmcnt(6)
	v_pk_mul_f32 v[86:87], v[136:137], v[86:87]
	v_pk_mul_f32 v[84:85], v[134:135], v[84:85]
	s_waitcnt vmcnt(5)
	v_pk_mul_f32 v[90:91], v[140:141], v[90:91]
	v_pk_mul_f32 v[88:89], v[138:139], v[88:89]
	s_waitcnt vmcnt(3)
	v_pk_mul_f32 v[94:95], v[144:145], v[94:95]
	v_pk_mul_f32 v[92:93], v[142:143], v[92:93]
	s_branch .LBB0_233
.LBB0_256:
	s_or_b64 exec, exec, s[10:11]
	s_and_b64 vcc, exec, s[8:9]
	s_cbranch_vccz .LBB0_281
	s_addk_i32 s29, 0x7ff
	s_abs_i32 s1, s29
	s_mul_hi_u32 s8, s1, s31
	s_mul_i32 s9, s8, s28
	s_ashr_i32 s0, s29, 31
	s_sub_i32 s1, s1, s9
	s_xor_b32 s0, s0, s30
	s_add_i32 s9, s8, 1
	s_sub_i32 s10, s1, s28
	s_cmp_ge_u32 s1, s28
	s_cselect_b32 s8, s9, s8
	s_cselect_b32 s1, s10, s1
	s_add_i32 s9, s8, 1
	s_cmp_ge_u32 s1, s28
	s_cselect_b32 s1, s9, s8
	s_xor_b32 s1, s1, s0
	s_sub_i32 s0, s1, s0
	v_mul_lo_u32 v48, s0, v99
	v_add_u32_e32 v0, 0x8000, v48
	v_add_u32_e32 v1, s0, v0
	v_min_i32_e32 v126, 0x8800, v1
	v_cmp_lt_i32_e32 vcc, v0, v126
	s_and_saveexec_b64 s[0:1], vcc
	s_cbranch_execz .LBB0_280
	v_ashrrev_i32_e32 v49, 31, v48
	v_readlane_b32 s36, v240, 8
	v_lshlrev_b32_e32 v2, 2, v160
	v_lshlrev_b64 v[50:51], 12, v[48:49]
	v_readlane_b32 s40, v240, 12
	v_readlane_b32 s41, v240, 13
	v_and_b32_e32 v54, 0xfc, v2
	v_mov_b32_e32 v53, 0
	v_lshl_add_u64 v[0:1], s[40:41], 0, v[50:51]
	v_lshlrev_b32_e32 v52, 2, v54
	v_lshl_add_u64 v[32:33], v[0:1], 0, v[52:53]
	global_load_dwordx4 v[0:3], v[32:33], off nt
	global_load_dwordx4 v[4:7], v[32:33], off offset:1024 nt
	global_load_dwordx4 v[8:11], v[32:33], off offset:2048 nt
	global_load_dwordx4 v[12:15], v[32:33], off offset:3072 nt
	v_add_u32_e32 v16, 0x8001, v48
	v_cmp_lt_i32_e32 vcc, v16, v126
	v_readlane_b32 s37, v240, 9
	v_readlane_b32 s38, v240, 10
	v_readlane_b32 s39, v240, 11
	v_readlane_b32 s42, v240, 14
	v_readlane_b32 s43, v240, 15
	v_readlane_b32 s44, v240, 16
	v_readlane_b32 s45, v240, 17
	v_readlane_b32 s46, v240, 18
	v_readlane_b32 s47, v240, 19
	v_readlane_b32 s48, v240, 20
	v_readlane_b32 s49, v240, 21
	v_readlane_b32 s50, v240, 22
	v_readlane_b32 s51, v240, 23
	s_and_saveexec_b64 s[8:9], vcc
	s_cbranch_execz .LBB0_260
	s_mov_b64 s[10:11], 0x1000
	s_waitcnt vmcnt(9)
	v_add_co_u32_e32 v20, vcc, 0x1000, v32
	v_lshl_add_u64 v[28:29], v[32:33], 0, s[10:11]
	s_waitcnt vmcnt(8)
	v_addc_co_u32_e32 v21, vcc, 0, v33, vcc
	global_load_dwordx4 v[16:19], v[28:29], off offset:1024 nt
	global_load_dwordx4 v[24:27], v[28:29], off offset:2048 nt
	s_nop 0
	global_load_dwordx4 v[20:23], v[20:21], off nt
	s_nop 0
	global_load_dwordx4 v[28:31], v[28:29], off offset:3072 nt
.LBB0_260:
	s_or_b64 exec, exec, s[8:9]
	v_add_u32_e32 v32, 0x8002, v48
	v_cmp_lt_i32_e32 vcc, v32, v126
	s_and_saveexec_b64 s[8:9], vcc
	s_cbranch_execz .LBB0_262
	v_readlane_b32 s36, v240, 8
	v_lshlrev_b64 v[32:33], 12, v[48:49]
	v_readlane_b32 s40, v240, 12
	v_readlane_b32 s41, v240, 13
	v_mov_b32_e32 v53, 0
	s_mov_b64 s[10:11], 0x2000
	v_lshl_add_u64 v[32:33], s[40:41], 0, v[32:33]
	v_lshl_add_u64 v[32:33], v[32:33], 0, v[52:53]
	v_add_co_u32_e32 v36, vcc, 0x2000, v32
	v_lshl_add_u64 v[44:45], v[32:33], 0, s[10:11]
	s_nop 0
	v_addc_co_u32_e32 v37, vcc, 0, v33, vcc
	global_load_dwordx4 v[32:35], v[44:45], off offset:1024 nt
	global_load_dwordx4 v[40:43], v[44:45], off offset:2048 nt
	s_nop 0
	global_load_dwordx4 v[36:39], v[36:37], off nt
	s_nop 0
	global_load_dwordx4 v[44:47], v[44:45], off offset:3072 nt
	v_readlane_b32 s37, v240, 9
	v_readlane_b32 s38, v240, 10
	v_readlane_b32 s39, v240, 11
	v_readlane_b32 s42, v240, 14
	v_readlane_b32 s43, v240, 15
	v_readlane_b32 s44, v240, 16
	v_readlane_b32 s45, v240, 17
	v_readlane_b32 s46, v240, 18
	v_readlane_b32 s47, v240, 19
	v_readlane_b32 s48, v240, 20
	v_readlane_b32 s49, v240, 21
	v_readlane_b32 s50, v240, 22
	v_readlane_b32 s51, v240, 23

.LBB0_265:
	v_add_u32_e32 v124, -3, v133
	v_cmp_lt_i32_e64 s[2:3], v124, v126
	s_and_saveexec_b64 s[16:17], s[2:3]
	s_cbranch_execz .LBB0_267
	global_load_dwordx4 v[60:63], v[118:119], off offset:-2048 nt
	global_load_dwordx4 v[56:59], v[118:119], off offset:-1024 nt
	global_load_dwordx4 v[52:55], v[118:119], off nt
	global_load_dwordx4 v[48:51], v[118:119], off offset:1024 nt
.LBB0_267:
	s_or_b64 exec, exec, s[16:17]
	s_xor_b64 s[14:15], s[14:15], -1
	s_andn2_b64 vcc, exec, s[14:15]
	s_cbranch_vccnz .LBB0_269
	global_load_dwordx4 v[80:83], v[102:103], off nt
	global_load_dwordx4 v[84:87], v[106:107], off nt
	global_load_dwordx4 v[88:91], v[110:111], off nt
	global_load_dwordx4 v[92:95], v[114:115], off nt
	global_load_dwordx4 v[136:139], v[100:101], off nt
	global_load_dwordx4 v[140:143], v[100:101], off offset:1024 nt
	global_load_dwordx4 v[64:67], v[104:105], off nt
	global_load_dwordx4 v[144:147], v[100:101], off offset:2048 nt
	global_load_dwordx4 v[68:71], v[108:109], off nt
	global_load_dwordx4 v[148:151], v[100:101], off offset:3072 nt
	global_load_dwordx4 v[72:75], v[112:113], off nt
	global_load_dwordx4 v[76:79], v[116:117], off nt
	s_waitcnt vmcnt(11)
	v_pk_add_f32 v[82:83], v[82:83], 1.0 op_sel_hi:[1,0]
	v_pk_add_f32 v[80:81], v[80:81], 1.0 op_sel_hi:[1,0]
	s_waitcnt vmcnt(10)
	v_pk_add_f32 v[86:87], v[86:87], 1.0 op_sel_hi:[1,0]
	v_pk_add_f32 v[84:85], v[84:85], 1.0 op_sel_hi:[1,0]
	s_waitcnt vmcnt(9)
	v_pk_add_f32 v[90:91], v[90:91], 1.0 op_sel_hi:[1,0]
	v_pk_add_f32 v[88:89], v[88:89], 1.0 op_sel_hi:[1,0]
	s_waitcnt vmcnt(8)
	v_pk_add_f32 v[94:95], v[94:95], 1.0 op_sel_hi:[1,0]
	v_pk_add_f32 v[92:93], v[92:93], 1.0 op_sel_hi:[1,0]
	s_waitcnt vmcnt(7)
	v_pk_mul_f32 v[82:83], v[138:139], v[82:83]
	v_pk_mul_f32 v[80:81], v[136:137], v[80:81]
	s_waitcnt vmcnt(6)
	v_pk_mul_f32 v[86:87], v[142:143], v[86:87]
	v_pk_mul_f32 v[84:85], v[140:141], v[84:85]
	s_waitcnt vmcnt(4)
	v_pk_mul_f32 v[90:91], v[146:147], v[90:91]
	v_pk_mul_f32 v[88:89], v[144:145], v[88:89]
	s_waitcnt vmcnt(2)
	v_pk_mul_f32 v[94:95], v[150:151], v[94:95]
	v_pk_mul_f32 v[92:93], v[148:149], v[92:93]
.LBB0_269:
	s_waitcnt vmcnt(2)
	v_mov_b32_e32 v136, v5
	v_mov_b32_e32 v137, v1
	v_mov_b32_e32 v124, v4
	v_mov_b32_e32 v125, v0
	v_pk_mul_f32 v[136:137], v[136:137], v[136:137]
	s_waitcnt vmcnt(0)
	v_mov_b32_e32 v138, v13
	v_pk_fma_f32 v[124:125], v[124:125], v[124:125], v[136:137]
	v_mov_b32_e32 v136, v6
	v_mov_b32_e32 v137, v2
	v_pk_fma_f32 v[124:125], v[136:137], v[136:137], v[124:125]
	v_mov_b32_e32 v136, v7
	v_mov_b32_e32 v137, v3
	v_mov_b32_e32 v139, v9
	v_pk_fma_f32 v[124:125], v[136:137], v[136:137], v[124:125]
	v_mov_b32_e32 v136, v12
	v_mov_b32_e32 v137, v8
	v_pk_mul_f32 v[138:139], v[138:139], v[138:139]
	v_add_f32_e32 v124, v124, v125
	v_pk_fma_f32 v[136:137], v[136:137], v[136:137], v[138:139]
	v_mov_b32_e32 v138, v14
	v_mov_b32_e32 v139, v10
	v_pk_fma_f32 v[136:137], v[138:139], v[138:139], v[136:137]
	v_mov_b32_e32 v138, v15
	v_mov_b32_e32 v139, v11
	v_pk_fma_f32 v[136:137], v[138:139], v[138:139], v[136:137]
	s_nop 0
	v_add_f32_e32 v124, v137, v124
	v_add_f32_e32 v124, v136, v124
	ds_bpermute_b32 v125, v127, v124
	s_waitcnt lgkmcnt(0)
	v_add_f32_e32 v124, v124, v125
	ds_bpermute_b32 v125, v128, v124
	s_waitcnt lgkmcnt(0)
	v_add_f32_e32 v124, v124, v125
	ds_bpermute_b32 v125, v129, v124
	s_waitcnt lgkmcnt(0)
	v_add_f32_e32 v124, v124, v125
	ds_bpermute_b32 v125, v130, v124
	s_waitcnt lgkmcnt(0)
	v_add_f32_e32 v124, v124, v125
	ds_bpermute_b32 v125, v131, v124
	s_waitcnt lgkmcnt(0)
	v_add_f32_e32 v124, v124, v125
	ds_bpermute_b32 v125, v132, v124
	s_waitcnt lgkmcnt(0)
	v_add_f32_e32 v124, v124, v125
	v_fmamk_f32 v124, v124, 0x3a800000, v134
	v_mul_f32_e32 v125, 0x4b800000, v124
	v_cmp_gt_f32_e32 vcc, s24, v124
	s_nop 1
	v_cndmask_b32_e32 v124, v124, v125, vcc
	v_rsq_f32_e32 v135, v124
	v_lshl_add_u64 v[124:125], v[120:121], 0, v[96:97]
	v_mul_f32_e32 v136, 0x45800000, v135
	v_cndmask_b32_e32 v136, v135, v136, vcc
	v_pk_mul_f32 v[138:139], v[0:1], v[136:137] op_sel_hi:[1,0]
	v_pk_mul_f32 v[140:141], v[2:3], v[136:137] op_sel_hi:[1,0]
	v_pk_fma_f32 v[138:139], v[80:81], v[138:139], v[64:65]
	v_pk_fma_f32 v[140:141], v[82:83], v[140:141], v[66:67]
	v_add_co_u32_e32 v124, vcc, s25, v124
	v_cvt_pk_bf16_f32 v138, v138, v139
	v_cvt_pk_bf16_f32 v139, v140, v141
	v_addc_co_u32_e32 v125, vcc, 0, v125, vcc
	global_store_dwordx2 v[124:125], v[138:139], off
	v_pk_mul_f32 v[138:139], v[4:5], v[136:137] op_sel_hi:[1,0]
	v_pk_mul_f32 v[140:141], v[6:7], v[136:137] op_sel_hi:[1,0]
	v_pk_fma_f32 v[138:139], v[84:85], v[138:139], v[68:69]
	v_pk_fma_f32 v[140:141], v[86:87], v[140:141], v[70:71]
	v_cvt_pk_bf16_f32 v138, v138, v139
	v_cvt_pk_bf16_f32 v139, v140, v141
	global_store_dwordx2 v[124:125], v[138:139], off offset:512
	v_pk_mul_f32 v[138:139], v[8:9], v[136:137] op_sel_hi:[1,0]
	v_pk_mul_f32 v[140:141], v[10:11], v[136:137] op_sel_hi:[1,0]
	v_pk_fma_f32 v[138:139], v[88:89], v[138:139], v[72:73]
	v_pk_fma_f32 v[140:141], v[90:91], v[140:141], v[74:75]
	v_cvt_pk_bf16_f32 v138, v138, v139
	v_cvt_pk_bf16_f32 v139, v140, v141
	global_store_dwordx2 v[124:125], v[138:139], off offset:1024
	v_pk_mul_f32 v[138:139], v[12:13], v[136:137] op_sel_hi:[1,0]
	v_pk_mul_f32 v[136:137], v[14:15], v[136:137] op_sel_hi:[1,0]
	v_pk_fma_f32 v[138:139], v[92:93], v[138:139], v[76:77]
	v_pk_fma_f32 v[136:137], v[94:95], v[136:137], v[78:79]
	v_cvt_pk_bf16_f32 v138, v138, v139
	v_cvt_pk_bf16_f32 v139, v136, v137
	global_store_dwordx2 v[124:125], v[138:139], off offset:1536
	v_add_u32_e32 v124, -5, v133
	v_cmp_lt_i32_e32 vcc, v124, v126
	v_add_u32_e32 v135, -2, v133
	s_and_saveexec_b64 s[14:15], vcc
	s_cbranch_execz .LBB0_273
	v_cmp_lt_i32_e32 vcc, v135, v126
	s_and_saveexec_b64 s[16:17], vcc
	s_cbranch_execz .LBB0_272
	v_add_co_u32_e32 v12, vcc, 0x1000, v118
	global_load_dwordx4 v[0:3], v[118:119], off offset:2048 nt
	global_load_dwordx4 v[4:7], v[118:119], off offset:3072 nt
	v_addc_co_u32_e32 v13, vcc, 0, v119, vcc
	global_load_dwordx4 v[8:11], v[12:13], off nt
	s_nop 0
	global_load_dwordx4 v[12:15], v[12:13], off offset:1024 nt

.LBB0_273:
	s_or_b64 exec, exec, s[14:15]
	v_add_u32_e32 v124, -4, v133
	v_cmp_lt_i32_e32 vcc, v124, v126
	s_and_saveexec_b64 s[14:15], vcc
	s_cbranch_execz .LBB0_277
	v_add_u32_e32 v125, -1, v133
	v_cmp_lt_i32_e32 vcc, v125, v126
	s_and_saveexec_b64 s[16:17], vcc
	s_cbranch_execz .LBB0_276
	v_add_co_u32_e32 v16, vcc, 0x1000, v118
	s_nop 1
	v_addc_co_u32_e32 v17, vcc, 0, v119, vcc
	v_add_co_u32_e32 v28, vcc, 0x2000, v118
	global_load_dwordx4 v[20:23], v[16:17], off offset:2048 nt
	s_nop 0
	global_load_dwordx4 v[16:19], v[16:17], off offset:3072 nt
	v_addc_co_u32_e32 v29, vcc, 0, v119, vcc
	global_load_dwordx4 v[24:27], v[28:29], off nt
	s_nop 0
	global_load_dwordx4 v[28:31], v[28:29], off offset:1024 nt

.LBB0_277:
	s_or_b64 exec, exec, s[14:15]
	s_and_saveexec_b64 s[14:15], s[2:3]
	s_cbranch_execz .LBB0_264
	v_cmp_lt_i32_e32 vcc, v133, v126
	s_and_saveexec_b64 s[2:3], vcc
	s_cbranch_execz .LBB0_263
	v_add_co_u32_e32 v32, vcc, 0x2000, v118
	s_nop 1
	v_addc_co_u32_e32 v33, vcc, 0, v119, vcc
	v_add_co_u32_e32 v44, vcc, 0x3000, v118
	global_load_dwordx4 v[36:39], v[32:33], off offset:2048 nt
	s_nop 0
	global_load_dwordx4 v[32:35], v[32:33], off offset:3072 nt
	v_addc_co_u32_e32 v45, vcc, 0, v119, vcc
	global_load_dwordx4 v[40:43], v[44:45], off nt
	s_nop 0
	global_load_dwordx4 v[44:47], v[44:45], off offset:1024 nt
	s_branch .LBB0_263

.LBB0_281:
	s_and_b64 vcc, exec, s[6:7]
	s_cbranch_vccz .LBB0_299
	s_lshr_b32 s8, s20, 2
	s_lshl_b32 s6, s8, 20
	s_lshl_b32 s16, s8, 8
	s_add_u32 s0, s22, 0x19b0000
	s_addc_u32 s1, s23, 0
	s_add_u32 s2, s22, 0x19b1000
	v_lshlrev_b32_e32 v118, 4, v160
	s_addc_u32 s3, s23, 0
	s_waitcnt vmcnt(6)
	v_and_b32_e32 v16, 0x3f0, v118
	global_load_dwordx4 v[32:35], v16, s[2:3] nt
	v_readlane_b32 s36, v240, 8
	v_or_b32_e32 v4, 0x400, v16
	s_waitcnt vmcnt(6)
	v_or_b32_e32 v8, 0x800, v16
	s_waitcnt vmcnt(5)
	v_or_b32_e32 v12, 0xc00, v16
	v_readlane_b32 s40, v240, 12
	v_readlane_b32 s48, v240, 20
	v_readlane_b32 s49, v240, 21
	v_lshrrev_b32_e32 v120, 1, v160
	global_load_dwordx4 v[36:39], v4, s[2:3] nt
	global_load_dwordx4 v[40:43], v8, s[2:3] nt
	global_load_dwordx4 v[44:47], v12, s[2:3] nt
	v_readlane_b32 s41, v240, 13
	global_load_dwordx4 v[98:101], v16, s[48:49] nt
	global_load_dwordx4 v[102:105], v16, s[48:49] offset:1024 nt
	global_load_dwordx4 v[106:109], v16, s[48:49] offset:2048 nt
	global_load_dwordx4 v[110:113], v16, s[48:49] offset:3072 nt
	v_lshrrev_b32_e32 v116, 3, v160
	v_and_b32_e32 v116, 56, v116
	s_and_b32 s9, s20, 3
	s_lshl_b32 s9, s9, 6
	v_add_u32_e32 v116, s9, v116
	global_load_dwordx4 v[0:3], v16, s[0:1] nt
	s_nop 0
	global_load_dwordx4 v[4:7], v4, s[0:1] nt
	s_nop 0
	global_load_dwordx4 v[8:11], v8, s[0:1] nt
	s_nop 0
	global_load_dwordx4 v[12:15], v12, s[0:1] nt
	s_add_u32 s0, s40, s6
	v_mov_b32_e32 v115, 0
	v_lshlrev_b32_e32 v114, 12, v116
	s_addc_u32 s1, s41, 0
	v_mov_b32_e32 v17, v115
	v_lshl_add_u64 v[18:19], s[0:1], 0, v[114:115]
	s_movk_i32 s9, 0x1000
	v_lshl_add_u64 v[16:17], v[18:19], 0, v[16:17]
	v_add_co_u32_e32 v18, vcc, s9, v16
	s_movk_i32 s2, 0x2000
	s_nop 0
	v_addc_co_u32_e32 v19, vcc, 0, v17, vcc
	v_add_co_u32_e32 v20, vcc, s2, v16
	s_movk_i32 s3, 0x3000
	s_nop 0
	v_addc_co_u32_e32 v21, vcc, 0, v17, vcc
	global_load_dwordx4 v[88:91], v[16:17], off nt
	global_load_dwordx4 v[84:87], v[16:17], off offset:1024 nt
	global_load_dwordx4 v[80:83], v[16:17], off offset:2048 nt
	global_load_dwordx4 v[76:79], v[16:17], off offset:3072 nt
	v_add_co_u32_e32 v16, vcc, s3, v16
	v_mbcnt_lo_u32_b32 v96, -1, 0
	s_nop 0
	v_addc_co_u32_e32 v17, vcc, 0, v17, vcc
	global_load_dwordx4 v[72:75], v[18:19], off offset:1024 nt
	global_load_dwordx4 v[68:71], v[18:19], off offset:2048 nt
	global_load_dwordx4 v[92:95], v[20:21], off offset:-4096 nt
	global_load_dwordx4 v[60:63], v[20:21], off nt
	global_load_dwordx4 v[56:59], v[20:21], off offset:1024 nt
	global_load_dwordx4 v[52:55], v[20:21], off offset:2048 nt
	global_load_dwordx4 v[48:51], v[20:21], off offset:3072 nt
	global_load_dwordx4 v[64:67], v[18:19], off offset:3072 nt
	global_load_dwordx4 v[28:31], v[16:17], off nt
	global_load_dwordx4 v[24:27], v[16:17], off offset:1024 nt
	s_nop 0
	global_load_dwordx4 v[20:23], v[16:17], off offset:2048 nt
	s_nop 0
	global_load_dwordx4 v[16:19], v[16:17], off offset:3072 nt
	v_mbcnt_hi_u32_b32 v117, -1, v96
	v_and_b32_e32 v96, 64, v117
	v_xor_b32_e32 v121, 32, v117
	v_add_u32_e32 v126, 64, v96
	v_cmp_lt_i32_e32 vcc, v121, v126
	s_mov_b64 s[2:3], 0x30bc000
	s_mov_b32 s10, 0
	v_lshlrev_b32_e32 v119, 2, v160
	v_mov_b32_e32 v127, 0x358637bd
	s_mov_b32 s11, 0x800000
	v_readlane_b32 s37, v240, 9
	v_readlane_b32 s38, v240, 10
	v_readlane_b32 s39, v240, 11
	v_readlane_b32 s42, v240, 14
	v_readlane_b32 s43, v240, 15
	v_readlane_b32 s44, v240, 16
	v_readlane_b32 s45, v240, 17
	v_readlane_b32 s46, v240, 18
	v_readlane_b32 s47, v240, 19
	v_readlane_b32 s50, v240, 22
	v_readlane_b32 s51, v240, 23
	s_waitcnt vmcnt(27)
	v_pk_add_f32 v[32:33], v[32:33], 1.0 op_sel_hi:[1,0]
	v_pk_add_f32 v[34:35], v[34:35], 1.0 op_sel_hi:[1,0]
	s_waitcnt vmcnt(26)
	v_pk_add_f32 v[38:39], v[38:39], 1.0 op_sel_hi:[1,0]
	s_waitcnt vmcnt(23)
	v_pk_mul_f32 v[98:99], v[98:99], v[32:33]
	v_cndmask_b32_e32 v32, v117, v121, vcc
	v_lshlrev_b32_e32 v121, 2, v32
	v_xor_b32_e32 v32, 16, v117
	v_cmp_lt_i32_e32 vcc, v32, v126
	v_pk_mul_f32 v[96:97], v[100:101], v[34:35]
	v_and_b32_e32 v34, 63, v160
	v_cndmask_b32_e32 v32, v117, v32, vcc
	v_lshlrev_b32_e32 v122, 2, v32
	v_xor_b32_e32 v32, 8, v117
	v_cmp_lt_i32_e32 vcc, v32, v126
	v_add_u32_e32 v33, s16, v116
	v_pk_add_f32 v[42:43], v[42:43], 1.0 op_sel_hi:[1,0]
	v_cndmask_b32_e32 v32, v117, v32, vcc
	v_lshlrev_b32_e32 v123, 2, v32
	v_xor_b32_e32 v32, 4, v117
	v_cmp_lt_i32_e32 vcc, v32, v126
	v_pk_add_f32 v[46:47], v[46:47], 1.0 op_sel_hi:[1,0]
	v_lshl_or_b32 v114, v34, 4, v114
	v_cndmask_b32_e32 v32, v117, v32, vcc
	v_lshlrev_b32_e32 v124, 2, v32
	v_xor_b32_e32 v32, 2, v117
	v_cmp_lt_i32_e32 vcc, v32, v126
	v_pk_add_f32 v[36:37], v[36:37], 1.0 op_sel_hi:[1,0]
	v_pk_add_f32 v[40:41], v[40:41], 1.0 op_sel_hi:[1,0]
	v_cndmask_b32_e32 v32, v117, v32, vcc
	v_lshlrev_b32_e32 v125, 2, v32
	v_xor_b32_e32 v32, 1, v117
	v_cmp_lt_i32_e32 vcc, v32, v126
	v_pk_add_f32 v[44:45], v[44:45], 1.0 op_sel_hi:[1,0]
	s_waitcnt vmcnt(22)
	v_pk_mul_f32 v[100:101], v[104:105], v[38:39]
	v_cndmask_b32_e32 v32, v117, v32, vcc
	v_lshlrev_b32_e32 v126, 2, v32
	v_lshlrev_b32_e32 v32, 3, v34
	v_lshl_or_b32 v32, v33, 11, v32
	v_add_u32_e32 v32, 0x4000000, v32
	v_mov_b32_e32 v33, v115
	v_lshl_add_u64 v[32:33], s[22:23], 0, v[32:33]
	s_waitcnt vmcnt(21)
	v_pk_mul_f32 v[104:105], v[108:109], v[42:43]
	s_waitcnt vmcnt(20)
	v_pk_mul_f32 v[108:109], v[112:113], v[46:47]
	v_lshl_add_u64 v[112:113], v[32:33], 0, s[2:3]
	v_lshl_add_u64 v[32:33], s[0:1], 0, v[114:115]
	s_mov_b64 s[0:1], 0x7c00
	v_pk_mul_f32 v[102:103], v[102:103], v[36:37]
	v_pk_mul_f32 v[106:107], v[106:107], v[40:41]
	v_pk_mul_f32 v[110:111], v[110:111], v[44:45]
	v_lshl_add_u64 v[114:115], v[32:33], 0, s[0:1]
	s_waitcnt vmcnt(12)
	v_mov_b64_e32 v[32:33], v[76:77]
	v_mov_b64_e32 v[36:37], v[80:81]
	v_mov_b64_e32 v[40:41], v[84:85]
	v_mov_b64_e32 v[44:45], v[88:89]
	s_mov_b64 s[0:1], 0x2000
	s_mov_b64 s[2:3], 0x4000
	v_mov_b64_e32 v[34:35], v[78:79]
	v_mov_b64_e32 v[38:39], v[82:83]
	v_mov_b64_e32 v[42:43], v[86:87]
	v_mov_b64_e32 v[46:47], v[90:91]
	s_branch .LBB0_284

.LBB0_284:
	v_mov_b32_e32 v128, v85
	v_mov_b32_e32 v129, v89
	v_mov_b32_e32 v116, v84
	v_mov_b32_e32 v117, v88
	v_pk_mul_f32 v[128:129], v[128:129], v[128:129]
	v_mov_b32_e32 v130, v77
	v_pk_fma_f32 v[116:117], v[116:117], v[116:117], v[128:129]
	v_mov_b32_e32 v128, v86
	v_mov_b32_e32 v129, v90
	v_pk_fma_f32 v[116:117], v[128:129], v[128:129], v[116:117]
	v_mov_b32_e32 v128, v87
	v_mov_b32_e32 v129, v91
	v_mov_b32_e32 v131, v81
	v_pk_fma_f32 v[116:117], v[128:129], v[128:129], v[116:117]
	v_mov_b32_e32 v128, v76
	v_mov_b32_e32 v129, v80
	v_pk_mul_f32 v[130:131], v[130:131], v[130:131]
	v_add_f32_e32 v116, v116, v117
	v_pk_fma_f32 v[128:129], v[128:129], v[128:129], v[130:131]
	v_mov_b32_e32 v130, v78
	v_mov_b32_e32 v131, v82
	v_pk_fma_f32 v[128:129], v[130:131], v[130:131], v[128:129]
	v_mov_b32_e32 v130, v79
	v_mov_b32_e32 v131, v83
	v_pk_fma_f32 v[128:129], v[130:131], v[130:131], v[128:129]
	s_cmp_gt_u32 s10, 3
	v_add_f32_e32 v116, v129, v116
	v_add_f32_e32 v116, v128, v116
	ds_bpermute_b32 v117, v121, v116
	s_cselect_b64 s[6:7], -1, 0
	s_cmp_lt_u32 s10, 4
	s_waitcnt lgkmcnt(0)
	v_add_f32_e32 v116, v116, v117
	ds_bpermute_b32 v117, v122, v116
	s_waitcnt lgkmcnt(0)
	v_add_f32_e32 v116, v116, v117
	ds_bpermute_b32 v117, v123, v116
	s_waitcnt lgkmcnt(0)
	v_add_f32_e32 v116, v116, v117
	ds_bpermute_b32 v117, v124, v116
	s_waitcnt lgkmcnt(0)
	v_add_f32_e32 v116, v116, v117
	ds_bpermute_b32 v117, v125, v116
	s_waitcnt lgkmcnt(0)
	v_add_f32_e32 v116, v116, v117
	ds_bpermute_b32 v117, v126, v116
	s_cbranch_scc0 .LBB0_286
	v_add_co_u32_e32 v32, vcc, 0xffffd000, v114
	s_nop 1
	v_addc_co_u32_e32 v33, vcc, -1, v115, vcc
	global_load_dwordx4 v[44:47], v[32:33], off offset:-3072 nt
	global_load_dwordx4 v[40:43], v[32:33], off offset:-2048 nt
	global_load_dwordx4 v[36:39], v[32:33], off offset:-1024 nt
	s_nop 0
	global_load_dwordx4 v[32:35], v[32:33], off nt
.LBB0_286:
	s_waitcnt lgkmcnt(0)
	v_add_f32_e32 v116, v116, v117
	v_fmamk_f32 v116, v116, 0x3a800000, v127
	v_mul_f32_e32 v117, 0x4b800000, v116
	v_cmp_gt_f32_e32 vcc, s11, v116
	s_waitcnt vmcnt(11)
	v_mov_b32_e32 v128, v73
	s_waitcnt vmcnt(9)
	v_mov_b32_e32 v129, v93
	v_cndmask_b32_e32 v116, v116, v117, vcc
	v_rsq_f32_e32 v116, v116
	v_pk_mul_f32 v[128:129], v[128:129], v[128:129]
	s_waitcnt vmcnt(4)
	v_mov_b32_e32 v130, v65
	v_mov_b32_e32 v131, v69
	v_mul_f32_e32 v117, 0x45800000, v116
	v_cndmask_b32_e32 v116, v116, v117, vcc
	v_pk_mul_f32 v[88:89], v[88:89], v[116:117] op_sel_hi:[1,0]
	v_pk_mul_f32 v[90:91], v[90:91], v[116:117] op_sel_hi:[1,0]
	v_pk_fma_f32 v[88:89], v[98:99], v[88:89], v[0:1]
	v_pk_fma_f32 v[90:91], v[96:97], v[90:91], v[2:3]
	v_cvt_pk_bf16_f32 v88, v88, v89
	v_cvt_pk_bf16_f32 v89, v90, v91
	v_mov_b32_e32 v90, v72
	v_mov_b32_e32 v91, v92
	v_pk_fma_f32 v[90:91], v[90:91], v[90:91], v[128:129]
	v_mov_b32_e32 v128, v74
	v_mov_b32_e32 v129, v94
	v_pk_fma_f32 v[90:91], v[128:129], v[128:129], v[90:91]
	v_mov_b32_e32 v128, v75
	v_mov_b32_e32 v129, v95
	v_pk_fma_f32 v[90:91], v[128:129], v[128:129], v[90:91]
	v_mov_b32_e32 v128, v64
	v_mov_b32_e32 v129, v68
	v_pk_mul_f32 v[130:131], v[130:131], v[130:131]
	v_add_f32_e32 v90, v90, v91
	v_pk_fma_f32 v[128:129], v[128:129], v[128:129], v[130:131]
	v_mov_b32_e32 v130, v66
	v_mov_b32_e32 v131, v70
	v_pk_fma_f32 v[128:129], v[130:131], v[130:131], v[128:129]
	v_mov_b32_e32 v130, v67
	v_mov_b32_e32 v131, v71
	v_pk_fma_f32 v[128:129], v[130:131], v[130:131], v[128:129]
	v_pk_mul_f32 v[84:85], v[84:85], v[116:117] op_sel_hi:[1,0]
	v_add_f32_e32 v90, v129, v90
	v_add_f32_e32 v90, v128, v90
	ds_bpermute_b32 v91, v121, v90
	v_pk_mul_f32 v[86:87], v[86:87], v[116:117] op_sel_hi:[1,0]
	v_pk_fma_f32 v[84:85], v[102:103], v[84:85], v[4:5]
	v_pk_fma_f32 v[86:87], v[100:101], v[86:87], v[6:7]
	v_cvt_pk_bf16_f32 v84, v84, v85
	v_cvt_pk_bf16_f32 v85, v86, v87
	s_waitcnt lgkmcnt(0)
	v_add_f32_e32 v86, v90, v91
	ds_bpermute_b32 v87, v122, v86
	v_pk_mul_f32 v[80:81], v[80:81], v[116:117] op_sel_hi:[1,0]
	v_pk_mul_f32 v[82:83], v[82:83], v[116:117] op_sel_hi:[1,0]
	v_pk_fma_f32 v[80:81], v[106:107], v[80:81], v[8:9]
	v_pk_fma_f32 v[82:83], v[104:105], v[82:83], v[10:11]
	s_waitcnt lgkmcnt(0)
	v_add_f32_e32 v86, v86, v87
	ds_bpermute_b32 v87, v123, v86
	v_cvt_pk_bf16_f32 v80, v80, v81
	v_cvt_pk_bf16_f32 v81, v82, v83
	v_pk_mul_f32 v[76:77], v[76:77], v[116:117] op_sel_hi:[1,0]
	v_pk_mul_f32 v[78:79], v[78:79], v[116:117] op_sel_hi:[1,0]
	s_waitcnt lgkmcnt(0)
	v_add_f32_e32 v82, v86, v87
	ds_bpermute_b32 v83, v124, v82
	v_pk_fma_f32 v[78:79], v[108:109], v[78:79], v[14:15]
	v_pk_fma_f32 v[76:77], v[110:111], v[76:77], v[12:13]
	s_cmp_gt_u32 s10, 2
	v_cvt_pk_bf16_f32 v76, v76, v77
	v_cvt_pk_bf16_f32 v77, v78, v79
	s_waitcnt lgkmcnt(0)
	v_add_f32_e32 v78, v82, v83
	ds_bpermute_b32 v79, v125, v78
	global_store_dwordx2 v[112:113], v[88:89], off
	global_store_dwordx2 v[112:113], v[84:85], off offset:512
	global_store_dwordx2 v[112:113], v[80:81], off offset:1024
	global_store_dwordx2 v[112:113], v[76:77], off offset:1536
	v_mov_b64_e32 v[90:91], v[66:67]
	v_mov_b64_e32 v[86:87], v[70:71]
	v_mov_b64_e32 v[82:83], v[74:75]
	s_waitcnt lgkmcnt(0)
	v_add_f32_e32 v116, v78, v79
	ds_bpermute_b32 v117, v126, v116
	v_mov_b64_e32 v[76:77], v[92:93]
	v_mov_b64_e32 v[88:89], v[64:65]
	v_mov_b64_e32 v[84:85], v[68:69]
	v_mov_b64_e32 v[80:81], v[72:73]
	v_mov_b64_e32 v[78:79], v[94:95]
	s_cbranch_scc1 .LBB0_288
	v_add_co_u32_e32 v88, vcc, 0xffffe000, v114
	s_nop 1
	v_addc_co_u32_e32 v89, vcc, -1, v115, vcc
	global_load_dwordx4 v[76:79], v[88:89], off offset:-3072 nt
	global_load_dwordx4 v[80:83], v[88:89], off offset:-2048 nt
	global_load_dwordx4 v[84:87], v[88:89], off offset:-1024 nt
	s_nop 0
	global_load_dwordx4 v[88:91], v[88:89], off nt
.LBB0_288:
	s_waitcnt lgkmcnt(0)
	v_add_f32_e32 v116, v116, v117
	v_fmamk_f32 v116, v116, 0x3a800000, v127
	v_mul_f32_e32 v117, 0x4b800000, v116
	v_cmp_gt_f32_e32 vcc, s11, v116
	v_mov_b32_e32 v128, v57
	v_mov_b32_e32 v129, v61
	v_cndmask_b32_e32 v116, v116, v117, vcc
	v_rsq_f32_e32 v116, v116
	v_pk_mul_f32 v[128:129], v[128:129], v[128:129]
	v_mov_b32_e32 v130, v49
	v_mov_b32_e32 v131, v53
	v_mul_f32_e32 v117, 0x45800000, v116
	v_cndmask_b32_e32 v116, v116, v117, vcc
	v_pk_mul_f32 v[92:93], v[92:93], v[116:117] op_sel_hi:[1,0]
	v_pk_mul_f32 v[94:95], v[94:95], v[116:117] op_sel_hi:[1,0]
	v_pk_fma_f32 v[92:93], v[98:99], v[92:93], v[0:1]
	v_pk_fma_f32 v[94:95], v[96:97], v[94:95], v[2:3]
	v_cvt_pk_bf16_f32 v92, v92, v93
	v_cvt_pk_bf16_f32 v93, v94, v95
	v_mov_b32_e32 v94, v56
	v_mov_b32_e32 v95, v60
	v_pk_fma_f32 v[94:95], v[94:95], v[94:95], v[128:129]
	v_mov_b32_e32 v128, v58
	v_mov_b32_e32 v129, v62
	v_pk_fma_f32 v[94:95], v[128:129], v[128:129], v[94:95]
	v_mov_b32_e32 v128, v59
	v_mov_b32_e32 v129, v63
	v_pk_fma_f32 v[94:95], v[128:129], v[128:129], v[94:95]
	v_mov_b32_e32 v128, v48
	v_mov_b32_e32 v129, v52
	v_pk_mul_f32 v[130:131], v[130:131], v[130:131]
	v_add_f32_e32 v94, v94, v95
	v_pk_fma_f32 v[128:129], v[128:129], v[128:129], v[130:131]
	v_mov_b32_e32 v130, v50
	v_mov_b32_e32 v131, v54
	v_pk_fma_f32 v[128:129], v[130:131], v[130:131], v[128:129]
	v_mov_b32_e32 v130, v51
	v_mov_b32_e32 v131, v55
	v_pk_fma_f32 v[128:129], v[130:131], v[130:131], v[128:129]
	v_pk_mul_f32 v[72:73], v[72:73], v[116:117] op_sel_hi:[1,0]
	v_add_f32_e32 v94, v129, v94
	v_add_f32_e32 v94, v128, v94
	ds_bpermute_b32 v95, v121, v94
	v_pk_mul_f32 v[74:75], v[74:75], v[116:117] op_sel_hi:[1,0]
	v_pk_fma_f32 v[72:73], v[102:103], v[72:73], v[4:5]
	v_pk_fma_f32 v[74:75], v[100:101], v[74:75], v[6:7]
	v_cvt_pk_bf16_f32 v72, v72, v73
	v_cvt_pk_bf16_f32 v73, v74, v75
	s_waitcnt lgkmcnt(0)
	v_add_f32_e32 v74, v94, v95
	ds_bpermute_b32 v75, v122, v74
	v_pk_mul_f32 v[68:69], v[68:69], v[116:117] op_sel_hi:[1,0]
	v_pk_mul_f32 v[70:71], v[70:71], v[116:117] op_sel_hi:[1,0]
	v_pk_fma_f32 v[68:69], v[106:107], v[68:69], v[8:9]
	v_pk_fma_f32 v[70:71], v[104:105], v[70:71], v[10:11]
	s_waitcnt lgkmcnt(0)
	v_add_f32_e32 v74, v74, v75
	ds_bpermute_b32 v75, v123, v74
	v_cvt_pk_bf16_f32 v68, v68, v69
	v_cvt_pk_bf16_f32 v69, v70, v71
	v_pk_mul_f32 v[64:65], v[64:65], v[116:117] op_sel_hi:[1,0]
	v_pk_mul_f32 v[66:67], v[66:67], v[116:117] op_sel_hi:[1,0]
	s_waitcnt lgkmcnt(0)
	v_add_f32_e32 v70, v74, v75
	ds_bpermute_b32 v71, v124, v70
	v_pk_fma_f32 v[66:67], v[108:109], v[66:67], v[14:15]
	v_pk_fma_f32 v[64:65], v[110:111], v[64:65], v[12:13]
	s_cmp_gt_u32 s10, 1
	v_cvt_pk_bf16_f32 v64, v64, v65
	v_cvt_pk_bf16_f32 v65, v66, v67
	s_waitcnt lgkmcnt(0)
	v_add_f32_e32 v66, v70, v71
	ds_bpermute_b32 v67, v125, v66
	global_store_dwordx2 v[112:113], v[92:93], off offset:2048
	global_store_dwordx2 v[112:113], v[72:73], off offset:2560
	global_store_dwordx2 v[112:113], v[68:69], off offset:3072
	global_store_dwordx2 v[112:113], v[64:65], off offset:3584
	v_mov_b64_e32 v[94:95], v[50:51]
	v_mov_b64_e32 v[74:75], v[54:55]
	v_mov_b64_e32 v[70:71], v[58:59]
	s_waitcnt lgkmcnt(0)
	v_add_f32_e32 v116, v66, v67
	ds_bpermute_b32 v117, v126, v116
	v_mov_b64_e32 v[66:67], v[62:63]
	v_mov_b64_e32 v[92:93], v[48:49]
	v_mov_b64_e32 v[72:73], v[52:53]
	v_mov_b64_e32 v[68:69], v[56:57]
	v_mov_b64_e32 v[64:65], v[60:61]
	s_cbranch_scc1 .LBB0_290
	v_add_co_u32_e32 v72, vcc, 0xfffff000, v114
	s_nop 1
	v_addc_co_u32_e32 v73, vcc, -1, v115, vcc
	global_load_dwordx4 v[64:67], v[72:73], off offset:-3072 nt
	global_load_dwordx4 v[68:71], v[72:73], off offset:-2048 nt
	s_nop 0
	global_load_dwordx4 v[72:75], v[72:73], off offset:-1024 nt
	s_nop 0
	global_load_dwordx4 v[92:95], v[114:115], off offset:-4096 nt
.LBB0_290:
	s_waitcnt lgkmcnt(0)
	v_add_f32_e32 v116, v116, v117
	v_fmamk_f32 v116, v116, 0x3a800000, v127
	v_mul_f32_e32 v117, 0x4b800000, v116
	v_cmp_gt_f32_e32 vcc, s11, v116
	s_waitcnt vmcnt(8)
	v_mov_b32_e32 v128, v17
	v_mov_b32_e32 v129, v21
	v_cndmask_b32_e32 v116, v116, v117, vcc
	v_rsq_f32_e32 v116, v116
	v_pk_mul_f32 v[128:129], v[128:129], v[128:129]
	s_cmp_gt_u32 s10, 0
	v_mul_f32_e32 v117, 0x45800000, v116
	v_cndmask_b32_e32 v116, v116, v117, vcc
	v_pk_mul_f32 v[60:61], v[60:61], v[116:117] op_sel_hi:[1,0]
	v_pk_mul_f32 v[62:63], v[62:63], v[116:117] op_sel_hi:[1,0]
	v_pk_fma_f32 v[60:61], v[98:99], v[60:61], v[0:1]
	v_pk_fma_f32 v[62:63], v[96:97], v[62:63], v[2:3]
	v_pk_mul_f32 v[56:57], v[56:57], v[116:117] op_sel_hi:[1,0]
	v_pk_mul_f32 v[58:59], v[58:59], v[116:117] op_sel_hi:[1,0]
	v_cvt_pk_bf16_f32 v60, v60, v61
	v_cvt_pk_bf16_f32 v61, v62, v63
	v_pk_fma_f32 v[58:59], v[100:101], v[58:59], v[6:7]
	v_pk_fma_f32 v[56:57], v[102:103], v[56:57], v[4:5]
	v_mov_b32_e32 v62, v25
	v_mov_b32_e32 v63, v29
	v_cvt_pk_bf16_f32 v56, v56, v57
	v_cvt_pk_bf16_f32 v57, v58, v59
	v_mov_b32_e32 v58, v24
	v_mov_b32_e32 v59, v28
	v_pk_mul_f32 v[62:63], v[62:63], v[62:63]
	v_pk_mul_f32 v[52:53], v[52:53], v[116:117] op_sel_hi:[1,0]
	v_pk_fma_f32 v[58:59], v[58:59], v[58:59], v[62:63]
	v_mov_b32_e32 v62, v26
	v_mov_b32_e32 v63, v30
	v_pk_fma_f32 v[58:59], v[62:63], v[62:63], v[58:59]
	v_mov_b32_e32 v62, v27
	v_mov_b32_e32 v63, v31
	v_pk_fma_f32 v[58:59], v[62:63], v[62:63], v[58:59]
	v_mov_b32_e32 v62, v16
	v_mov_b32_e32 v63, v20
	v_pk_fma_f32 v[62:63], v[62:63], v[62:63], v[128:129]
	v_mov_b32_e32 v128, v18
	v_mov_b32_e32 v129, v22
	v_pk_fma_f32 v[62:63], v[128:129], v[128:129], v[62:63]
	v_mov_b32_e32 v128, v19
	v_mov_b32_e32 v129, v23
	v_pk_fma_f32 v[62:63], v[128:129], v[128:129], v[62:63]
	v_add_f32_e32 v58, v58, v59
	v_add_f32_e32 v58, v63, v58
	v_add_f32_e32 v58, v62, v58
	ds_bpermute_b32 v59, v121, v58
	v_pk_mul_f32 v[54:55], v[54:55], v[116:117] op_sel_hi:[1,0]
	v_pk_fma_f32 v[52:53], v[106:107], v[52:53], v[8:9]
	v_pk_fma_f32 v[54:55], v[104:105], v[54:55], v[10:11]
	v_cvt_pk_bf16_f32 v52, v52, v53
	s_waitcnt lgkmcnt(0)
	v_add_f32_e32 v58, v58, v59
	ds_bpermute_b32 v59, v122, v58
	v_cvt_pk_bf16_f32 v53, v54, v55
	v_pk_mul_f32 v[48:49], v[48:49], v[116:117] op_sel_hi:[1,0]
	v_pk_mul_f32 v[50:51], v[50:51], v[116:117] op_sel_hi:[1,0]
	v_pk_fma_f32 v[48:49], v[110:111], v[48:49], v[12:13]
	s_waitcnt lgkmcnt(0)
	v_add_f32_e32 v54, v58, v59
	ds_bpermute_b32 v55, v123, v54
	v_pk_fma_f32 v[50:51], v[108:109], v[50:51], v[14:15]
	v_cvt_pk_bf16_f32 v48, v48, v49
	v_cvt_pk_bf16_f32 v49, v50, v51
	v_add_co_u32_e32 v116, vcc, s9, v112
	s_waitcnt lgkmcnt(0)
	v_add_f32_e32 v50, v54, v55
	ds_bpermute_b32 v51, v124, v50
	v_addc_co_u32_e32 v117, vcc, 0, v113, vcc
	global_store_dwordx2 v[116:117], v[60:61], off
	global_store_dwordx2 v[116:117], v[56:57], off offset:512
	global_store_dwordx2 v[116:117], v[52:53], off offset:1024
	global_store_dwordx2 v[116:117], v[48:49], off offset:1536
	v_mov_b64_e32 v[62:63], v[18:19]
	s_waitcnt lgkmcnt(0)
	v_add_f32_e32 v50, v50, v51
	ds_bpermute_b32 v51, v125, v50
	v_mov_b64_e32 v[58:59], v[22:23]
	v_mov_b64_e32 v[54:55], v[26:27]
	v_mov_b64_e32 v[60:61], v[16:17]
	v_mov_b64_e32 v[56:57], v[20:21]
	s_waitcnt lgkmcnt(0)
	v_add_f32_e32 v128, v50, v51
	ds_bpermute_b32 v129, v126, v128
	v_mov_b64_e32 v[50:51], v[30:31]
	v_mov_b64_e32 v[52:53], v[24:25]
	v_mov_b64_e32 v[48:49], v[28:29]
	s_cbranch_scc1 .LBB0_283
	global_load_dwordx4 v[48:51], v[114:115], off offset:-3072 nt
	global_load_dwordx4 v[52:55], v[114:115], off offset:-2048 nt
	global_load_dwordx4 v[56:59], v[114:115], off offset:-1024 nt
	global_load_dwordx4 v[60:63], v[114:115], off nt
	s_branch .LBB0_283
